# attention A/B tile loads via SGPR base + 32-bit lane offset (no 64-bit VALU address math); shorter indexer key conversion
# speedup vs baseline: 1.0366x; 1.0080x over previous
; #define LAS __attribute__((address_space(3)))
; #define GAS __attribute__((address_space(1)))
; __device__ void indexer_item(LAS unsigned char* lds, const bf16_t* Qi, const bf16_t* Ki, const float* Wi, unsigned* maskout, int qt) {
;     ...
;     for (int it = 0; it < niter; ++it) {
;         const int kb = it * 256 + wid * 32;
;         bf16x8 kf[2][2];
; #pragma unroll
;         for (int st = 0; st < 2; ++st)
; #pragma unroll
;             for (int ks = 0; ks < 2; ++ks) kf[st][ks] = kn[st][ks];
;         { const int itn = (it + 1 < niter) ? it + 1 : it; const int kbn = itn * 256 + wid * 32;
; #pragma unroll
;           for (int st = 0; st < 2; ++st)
; #pragma unroll
;             for (int ks = 0; ks < 2; ++ks) kn[st][ks] = *(const GAS bf16x8*)(Ki + (size_t)(kbn + 16 * st + q) * 64 + ks * 32 + quad * 8); }
;         const f32x4 z4 = {0.f, 0.f, 0.f, 0.f};
;         f32x4 sc0, sc1, c0, c1;
;         { const bf16x8 qa = *(const LAS bf16x8*)(qrow + 16 * 128), qb2 = *(const LAS bf16x8*)(qrow + 16 * 128 + 64);
;           sc0 = __builtin_amdgcn_mfma_f32_16x16x32_bf16(kf[0][0], qa, z4, 0, 0, 0); sc0 = __builtin_amdgcn_mfma_f32_16x16x32_bf16(kf[0][1], qb2, sc0, 0, 0, 0);
;           sc1 = __builtin_amdgcn_mfma_f32_16x16x32_bf16(kf[1][0], qa, z4, 0, 0, 0); sc1 = __builtin_amdgcn_mfma_f32_16x16x32_bf16(kf[1][1], qb2, sc1, 0, 0, 0); }
;         { const bf16x8 qa = *(const LAS bf16x8*)(qrow), qb2 = *(const LAS bf16x8*)(qrow + 64);
;           c0 = __builtin_amdgcn_mfma_f32_16x16x32_bf16(kf[0][0], qa, z4, 0, 0, 0); c0 = __builtin_amdgcn_mfma_f32_16x16x32_bf16(kf[0][1], qb2, c0, 0, 0, 0);
;           c1 = __builtin_amdgcn_mfma_f32_16x16x32_bf16(kf[1][0], qa, z4, 0, 0, 0); c1 = __builtin_amdgcn_mfma_f32_16x16x32_bf16(kf[1][1], qb2, c1, 0, 0, 0); }
; #pragma unroll
;         for (int hd = 0; hd < 16; ++hd) {
;             f32x4 n0 = z4, n1 = z4;
;             if (hd < 15) {
;                 const bf16x8 qa = *(const LAS bf16x8*)(qrow + (hd + 1) * 128), qb2 = *(const LAS bf16x8*)(qrow + (hd + 1) * 128 + 64);
;                 n0 = __builtin_amdgcn_mfma_f32_16x16x32_bf16(kf[0][0], qa, z4, 0, 0, 0); n0 = __builtin_amdgcn_mfma_f32_16x16x32_bf16(kf[0][1], qb2, n0, 0, 0, 0);
;                 n1 = __builtin_amdgcn_mfma_f32_16x16x32_bf16(kf[1][0], qa, z4, 0, 0, 0); n1 = __builtin_amdgcn_mfma_f32_16x16x32_bf16(kf[1][1], qb2, n1, 0, 0, 0);
;             }
;             if (hd < 15)
.LBB0_636:
	s_waitcnt vmcnt(3)
	v_mov_b64_e32 v[42:43], v[30:31]
	s_waitcnt vmcnt(1)
	v_mov_b64_e32 v[50:51], v[22:23]
	v_mov_b64_e32 v[40:41], v[28:29]
	v_mov_b64_e32 v[48:49], v[20:21]
	ds_read_b128 v[28:31], v103 offset:2048
	ds_read_b128 v[32:35], v103 offset:2112
	v_mov_b64_e32 v[46:47], v[18:19]
	s_waitcnt vmcnt(0)
	v_mov_b64_e32 v[54:55], v[26:27]
	v_mov_b64_e32 v[44:45], v[16:17]
	v_mov_b64_e32 v[52:53], v[24:25]
	s_waitcnt lgkmcnt(1)
	v_mfma_f32_16x16x32_bf16 v[36:39], v[40:43], v[28:31], 0
	s_mov_b32 s28, s90
	s_add_i32 s90, s90, 1
	s_cmp_lt_i32 s90, s89
	v_mfma_f32_16x16x32_bf16 v[16:19], v[48:51], v[28:31], 0
	s_cselect_b32 s10, s90, s28
	v_lshl_add_u32 v68, s10, 8, v62
	v_ashrrev_i32_e32 v69, 31, v68
	s_waitcnt lgkmcnt(0)
	v_mfma_f32_16x16x32_bf16 v[36:39], v[44:47], v[32:35], v[36:39]
	v_mfma_f32_16x16x32_bf16 v[32:35], v[52:55], v[32:35], v[16:19]
	s_nop 2
	ds_read_b128 v[16:19], v103
	ds_read_b128 v[20:23], v103 offset:64
	ds_read_b128 v[108:111], v103 offset:192
	s_waitcnt lgkmcnt(2)
	v_mfma_f32_16x16x32_bf16 v[24:27], v[40:43], v[16:19], 0
	s_waitcnt lgkmcnt(1)
	v_mfma_f32_16x16x32_bf16 v[64:67], v[44:47], v[20:23], v[24:27]
	s_nop 5
	ds_read_b128 v[24:27], v103 offset:128
	v_mfma_f32_16x16x32_bf16 v[16:19], v[48:51], v[16:19], 0
	v_mfma_f32_16x16x32_bf16 v[104:107], v[52:55], v[20:23], v[16:19]
	s_waitcnt lgkmcnt(0)
	v_mfma_f32_16x16x32_bf16 v[20:23], v[40:43], v[24:27], 0
	s_nop 4
	v_lshlrev_b64 v[16:17], 7, v[68:69]
	v_lshl_add_u64 v[16:17], v[60:61], 0, v[16:17]
	global_load_dwordx4 v[28:31], v[16:17], off
	s_nop 0
	global_load_dwordx4 v[16:19], v[16:17], off offset:64
	v_mfma_f32_16x16x32_bf16 v[112:115], v[44:47], v[108:111], v[20:23]
	s_nop 2
	v_or_b32_e32 v20, 16, v68
	v_mfma_f32_16x16x32_bf16 v[116:119], v[48:51], v[24:27], 0
	v_ashrrev_i32_e32 v21, 31, v20
	v_lshlrev_b64 v[20:21], 7, v[20:21]
	v_lshl_add_u64 v[24:25], v[60:61], 0, v[20:21]
	v_mov_b32_e32 v68, v35
	global_load_dwordx4 v[20:23], v[24:25], off
	s_nop 0
	global_load_dwordx4 v[24:27], v[24:25], off offset:64
	v_mfma_f32_16x16x32_bf16 v[108:111], v[52:55], v[108:111], v[116:119]
	v_fma_f32 v36, v84, |v64|, v36
	v_fma_f32 v37, v84, |v65|, v37
	v_fma_f32 v38, v84, |v66|, v38
	v_fma_f32 v39, v84, |v67|, v39
	v_fma_f32 v32, v84, |v104|, v32
	v_fma_f32 v33, v84, |v105|, v33
	v_fma_f32 v34, v84, |v106|, v34
	v_fma_f32 v68, v84, |v107|, v68
	ds_read_b128 v[240:243], v103 offset:256
	ds_read_b128 v[244:247], v103 offset:320
	ds_read_b128 v[248:251], v103 offset:384
	ds_read_b128 v[252:255], v103 offset:448
	s_waitcnt lgkmcnt(3)
	v_mfma_f32_16x16x32_bf16 v[116:119], v[40:43], v[240:243], 0
	v_mfma_f32_16x16x32_bf16 v[64:67], v[48:51], v[240:243], 0
	s_waitcnt lgkmcnt(2)
	v_mfma_f32_16x16x32_bf16 v[116:119], v[44:47], v[244:247], v[116:119]
	v_mfma_f32_16x16x32_bf16 v[64:67], v[52:55], v[244:247], v[64:67]
	v_fma_f32 v36, v85, |v112|, v36
	v_fma_f32 v37, v85, |v113|, v37
	v_fma_f32 v38, v85, |v114|, v38
	v_fma_f32 v39, v85, |v115|, v39
	v_fma_f32 v32, v85, |v108|, v32
	v_fma_f32 v33, v85, |v109|, v33
	v_fma_f32 v34, v85, |v110|, v34
	v_fma_f32 v68, v85, |v111|, v68
	ds_read_b128 v[240:243], v103 offset:512
	ds_read_b128 v[244:247], v103 offset:576
	s_waitcnt lgkmcnt(3)
	v_mfma_f32_16x16x32_bf16 v[112:115], v[40:43], v[248:251], 0
	v_mfma_f32_16x16x32_bf16 v[104:107], v[48:51], v[248:251], 0
	s_waitcnt lgkmcnt(2)
	v_mfma_f32_16x16x32_bf16 v[112:115], v[44:47], v[252:255], v[112:115]
	v_mfma_f32_16x16x32_bf16 v[104:107], v[52:55], v[252:255], v[104:107]
	v_fma_f32 v36, v86, |v116|, v36
	v_fma_f32 v37, v86, |v117|, v37
	v_fma_f32 v38, v86, |v118|, v38
	v_fma_f32 v39, v86, |v119|, v39
	v_fma_f32 v32, v86, |v64|, v32
	v_fma_f32 v33, v86, |v65|, v33
	v_fma_f32 v34, v86, |v66|, v34
	v_fma_f32 v68, v86, |v67|, v68
	ds_read_b128 v[248:251], v103 offset:640
	ds_read_b128 v[252:255], v103 offset:704
	s_waitcnt lgkmcnt(3)
	v_mfma_f32_16x16x32_bf16 v[116:119], v[40:43], v[240:243], 0
	v_mfma_f32_16x16x32_bf16 v[64:67], v[48:51], v[240:243], 0
	s_waitcnt lgkmcnt(2)
	v_mfma_f32_16x16x32_bf16 v[116:119], v[44:47], v[244:247], v[116:119]
	v_mfma_f32_16x16x32_bf16 v[64:67], v[52:55], v[244:247], v[64:67]
	v_fma_f32 v36, v87, |v112|, v36
	v_fma_f32 v37, v87, |v113|, v37
	v_fma_f32 v38, v87, |v114|, v38
	v_fma_f32 v39, v87, |v115|, v39
	v_fma_f32 v32, v87, |v104|, v32
	v_fma_f32 v33, v87, |v105|, v33
	v_fma_f32 v34, v87, |v106|, v34
	v_fma_f32 v68, v87, |v107|, v68
	ds_read_b128 v[240:243], v103 offset:768
	ds_read_b128 v[244:247], v103 offset:832
	s_waitcnt lgkmcnt(3)
	v_mfma_f32_16x16x32_bf16 v[112:115], v[40:43], v[248:251], 0
	v_mfma_f32_16x16x32_bf16 v[104:107], v[48:51], v[248:251], 0
	s_waitcnt lgkmcnt(2)
	v_mfma_f32_16x16x32_bf16 v[112:115], v[44:47], v[252:255], v[112:115]
	v_mfma_f32_16x16x32_bf16 v[104:107], v[52:55], v[252:255], v[104:107]
	v_fma_f32 v36, v88, |v116|, v36
	v_fma_f32 v37, v88, |v117|, v37
	v_fma_f32 v38, v88, |v118|, v38
	v_fma_f32 v39, v88, |v119|, v39
	v_fma_f32 v32, v88, |v64|, v32
	v_fma_f32 v33, v88, |v65|, v33
	v_fma_f32 v34, v88, |v66|, v34
	v_fma_f32 v68, v88, |v67|, v68
	ds_read_b128 v[248:251], v103 offset:896
	ds_read_b128 v[252:255], v103 offset:960
	s_waitcnt lgkmcnt(3)
	v_mfma_f32_16x16x32_bf16 v[116:119], v[40:43], v[240:243], 0
	v_mfma_f32_16x16x32_bf16 v[64:67], v[48:51], v[240:243], 0
	s_waitcnt lgkmcnt(2)
	v_mfma_f32_16x16x32_bf16 v[116:119], v[44:47], v[244:247], v[116:119]
	v_mfma_f32_16x16x32_bf16 v[64:67], v[52:55], v[244:247], v[64:67]
	v_fma_f32 v36, v89, |v112|, v36
	v_fma_f32 v37, v89, |v113|, v37
	v_fma_f32 v38, v89, |v114|, v38
	v_fma_f32 v39, v89, |v115|, v39
	v_fma_f32 v32, v89, |v104|, v32
	v_fma_f32 v33, v89, |v105|, v33
	v_fma_f32 v34, v89, |v106|, v34
	v_fma_f32 v68, v89, |v107|, v68
	ds_read_b128 v[240:243], v103 offset:1024
	ds_read_b128 v[244:247], v103 offset:1088
	s_waitcnt lgkmcnt(3)
; #define LAS __attribute__((address_space(3)))
; __device__ void indexer_item(LAS unsigned char* lds, const bf16_t* Qi, const bf16_t* Ki, const float* Wi, unsigned* maskout, int qt) {
;     ...
; #pragma unroll
;         for (int hd = 0; hd < 16; ++hd) {
;             f32x4 n0 = z4, n1 = z4;
;             if (hd < 15) {
;                 const bf16x8 qa = *(const LAS bf16x8*)(qrow + (hd + 1) * 128), qb2 = *(const LAS bf16x8*)(qrow + (hd + 1) * 128 + 64);
;                 n0 = __builtin_amdgcn_mfma_f32_16x16x32_bf16(kf[0][0], qa, z4, 0, 0, 0); n0 = __builtin_amdgcn_mfma_f32_16x16x32_bf16(kf[0][1], qb2, n0, 0, 0, 0);
;                 n1 = __builtin_amdgcn_mfma_f32_16x16x32_bf16(kf[1][0], qa, z4, 0, 0, 0); n1 = __builtin_amdgcn_mfma_f32_16x16x32_bf16(kf[1][1], qb2, n1, 0, 0, 0);
;             }
;             if (hd < 15)
;                 asm volatile("v_fma_f32 %0, %16, |%8|, %0\n\tv_fma_f32 %1, %16, |%9|, %1\n\tv_fma_f32 %2, %16, |%10|, %2\n\tv_fma_f32 %3, %16, |%11|, %3\n\t"
;                              "v_fma_f32 %4, %16, |%12|, %4\n\tv_fma_f32 %5, %16, |%13|, %5\n\tv_fma_f32 %6, %16, |%14|, %6\n\tv_fma_f32 %7, %16, |%15|, %7"
;                              : "+v"(sc0[0]), "+v"(sc0[1]), "+v"(sc0[2]), "+v"(sc0[3]), "+v"(sc1[0]), "+v"(sc1[1]), "+v"(sc1[2]), "+v"(sc1[3])
;                              : "v"(c0[0]), "v"(c0[1]), "v"(c0[2]), "v"(c0[3]), "v"(c1[0]), "v"(c1[1]), "v"(c1[2]), "v"(c1[3]), "v"(wv[hd]), "v"(n0), "v"(n1));
;             else
;                 asm volatile("s_nop 15\n\ts_nop 15\n\t"
;                              "v_fma_f32 %0, %16, |%8|, %0\n\tv_fma_f32 %1, %16, |%9|, %1\n\tv_fma_f32 %2, %16, |%10|, %2\n\tv_fma_f32 %3, %16, |%11|, %3\n\t"
;                              "v_fma_f32 %4, %16, |%12|, %4\n\tv_fma_f32 %5, %16, |%13|, %5\n\tv_fma_f32 %6, %16, |%14|, %6\n\tv_fma_f32 %7, %16, |%15|, %7"
;                              : "+v"(sc0[0]), "+v"(sc0[1]), "+v"(sc0[2]), "+v"(sc0[3]), "+v"(sc1[0]), "+v"(sc1[1]), "+v"(sc1[2]), "+v"(sc1[3])
;                              : "v"(c0[0]), "v"(c0[1]), "v"(c0[2]), "v"(c0[3]), "v"(c1[0]), "v"(c1[1]), "v"(c1[2]), "v"(c1[3]), "v"(wv[hd]));
;             c0 = n0; c1 = n1;
;         }
	v_mfma_f32_16x16x32_bf16 v[112:115], v[40:43], v[248:251], 0
	v_mfma_f32_16x16x32_bf16 v[104:107], v[48:51], v[248:251], 0
	s_waitcnt lgkmcnt(2)
	v_mfma_f32_16x16x32_bf16 v[112:115], v[44:47], v[252:255], v[112:115]
	v_mfma_f32_16x16x32_bf16 v[104:107], v[52:55], v[252:255], v[104:107]
	v_fma_f32 v36, v90, |v116|, v36
	v_fma_f32 v37, v90, |v117|, v37
	v_fma_f32 v38, v90, |v118|, v38
	v_fma_f32 v39, v90, |v119|, v39
	v_fma_f32 v32, v90, |v64|, v32
	v_fma_f32 v33, v90, |v65|, v33
	v_fma_f32 v34, v90, |v66|, v34
	v_fma_f32 v68, v90, |v67|, v68
	ds_read_b128 v[248:251], v103 offset:1152
	ds_read_b128 v[252:255], v103 offset:1216
	s_waitcnt lgkmcnt(3)
	v_mfma_f32_16x16x32_bf16 v[116:119], v[40:43], v[240:243], 0
	v_mfma_f32_16x16x32_bf16 v[64:67], v[48:51], v[240:243], 0
	s_waitcnt lgkmcnt(2)
	v_mfma_f32_16x16x32_bf16 v[116:119], v[44:47], v[244:247], v[116:119]
	v_mfma_f32_16x16x32_bf16 v[64:67], v[52:55], v[244:247], v[64:67]
	v_fma_f32 v36, v91, |v112|, v36
	v_fma_f32 v37, v91, |v113|, v37
	v_fma_f32 v38, v91, |v114|, v38
	v_fma_f32 v39, v91, |v115|, v39
	v_fma_f32 v32, v91, |v104|, v32
	v_fma_f32 v33, v91, |v105|, v33
	v_fma_f32 v34, v91, |v106|, v34
	v_fma_f32 v68, v91, |v107|, v68
	ds_read_b128 v[240:243], v103 offset:1280
	ds_read_b128 v[244:247], v103 offset:1344
	s_waitcnt lgkmcnt(3)
	v_mfma_f32_16x16x32_bf16 v[112:115], v[40:43], v[248:251], 0
	v_mfma_f32_16x16x32_bf16 v[104:107], v[48:51], v[248:251], 0
	s_waitcnt lgkmcnt(2)
	v_mfma_f32_16x16x32_bf16 v[112:115], v[44:47], v[252:255], v[112:115]
	v_mfma_f32_16x16x32_bf16 v[104:107], v[52:55], v[252:255], v[104:107]
	v_fma_f32 v36, v92, |v116|, v36
	v_fma_f32 v37, v92, |v117|, v37
	v_fma_f32 v38, v92, |v118|, v38
	v_fma_f32 v39, v92, |v119|, v39
	v_fma_f32 v32, v92, |v64|, v32
	v_fma_f32 v33, v92, |v65|, v33
	v_fma_f32 v34, v92, |v66|, v34
	v_fma_f32 v68, v92, |v67|, v68
	ds_read_b128 v[248:251], v103 offset:1408
	ds_read_b128 v[252:255], v103 offset:1472
	s_waitcnt lgkmcnt(3)
	v_mfma_f32_16x16x32_bf16 v[116:119], v[40:43], v[240:243], 0
	v_mfma_f32_16x16x32_bf16 v[64:67], v[48:51], v[240:243], 0
	s_waitcnt lgkmcnt(2)
	v_mfma_f32_16x16x32_bf16 v[116:119], v[44:47], v[244:247], v[116:119]
	v_mfma_f32_16x16x32_bf16 v[64:67], v[52:55], v[244:247], v[64:67]
	v_fma_f32 v36, v93, |v112|, v36
	v_fma_f32 v37, v93, |v113|, v37
	v_fma_f32 v38, v93, |v114|, v38
	v_fma_f32 v39, v93, |v115|, v39
	v_fma_f32 v32, v93, |v104|, v32
	v_fma_f32 v33, v93, |v105|, v33
	v_fma_f32 v34, v93, |v106|, v34
	v_fma_f32 v68, v93, |v107|, v68
	ds_read_b128 v[240:243], v103 offset:1536
	ds_read_b128 v[244:247], v103 offset:1600
	s_waitcnt lgkmcnt(3)
	v_mfma_f32_16x16x32_bf16 v[112:115], v[40:43], v[248:251], 0
	v_mfma_f32_16x16x32_bf16 v[104:107], v[48:51], v[248:251], 0
	s_waitcnt lgkmcnt(2)
	v_mfma_f32_16x16x32_bf16 v[112:115], v[44:47], v[252:255], v[112:115]
	v_mfma_f32_16x16x32_bf16 v[104:107], v[52:55], v[252:255], v[104:107]
	v_fma_f32 v36, v94, |v116|, v36
	v_fma_f32 v37, v94, |v117|, v37
	v_fma_f32 v38, v94, |v118|, v38
	v_fma_f32 v39, v94, |v119|, v39
	v_fma_f32 v32, v94, |v64|, v32
	v_fma_f32 v33, v94, |v65|, v33
	v_fma_f32 v34, v94, |v66|, v34
	v_fma_f32 v68, v94, |v67|, v68
	ds_read_b128 v[248:251], v103 offset:1664
	ds_read_b128 v[252:255], v103 offset:1728
	s_waitcnt lgkmcnt(3)
	v_mfma_f32_16x16x32_bf16 v[116:119], v[40:43], v[240:243], 0
	v_mfma_f32_16x16x32_bf16 v[64:67], v[48:51], v[240:243], 0
	s_waitcnt lgkmcnt(2)
	v_mfma_f32_16x16x32_bf16 v[116:119], v[44:47], v[244:247], v[116:119]
	v_mfma_f32_16x16x32_bf16 v[64:67], v[52:55], v[244:247], v[64:67]
	v_fma_f32 v36, v95, |v112|, v36
	v_fma_f32 v37, v95, |v113|, v37
	v_fma_f32 v38, v95, |v114|, v38
	v_fma_f32 v39, v95, |v115|, v39
	v_fma_f32 v32, v95, |v104|, v32
	v_fma_f32 v33, v95, |v105|, v33
	v_fma_f32 v34, v95, |v106|, v34
	v_fma_f32 v68, v95, |v107|, v68
	ds_read_b128 v[240:243], v103 offset:1792
	ds_read_b128 v[244:247], v103 offset:1856
	s_waitcnt lgkmcnt(3)
	v_mfma_f32_16x16x32_bf16 v[112:115], v[40:43], v[248:251], 0
	v_mfma_f32_16x16x32_bf16 v[104:107], v[48:51], v[248:251], 0
	s_waitcnt lgkmcnt(2)
; __device__ void indexer_item(LAS unsigned char* lds, const bf16_t* Qi, const bf16_t* Ki, const float* Wi, unsigned* maskout, int qt) {
;     ...
;         for (int hd = 0; hd < 16; ++hd) {
;             f32x4 n0 = z4, n1 = z4;
;             if (hd < 15) {
;                 const bf16x8 qa = *(const LAS bf16x8*)(qrow + (hd + 1) * 128), qb2 = *(const LAS bf16x8*)(qrow + (hd + 1) * 128 + 64);
;                 n0 = __builtin_amdgcn_mfma_f32_16x16x32_bf16(kf[0][0], qa, z4, 0, 0, 0); n0 = __builtin_amdgcn_mfma_f32_16x16x32_bf16(kf[0][1], qb2, n0, 0, 0, 0);
;                 n1 = __builtin_amdgcn_mfma_f32_16x16x32_bf16(kf[1][0], qa, z4, 0, 0, 0); n1 = __builtin_amdgcn_mfma_f32_16x16x32_bf16(kf[1][1], qb2, n1, 0, 0, 0);
;             }
;             if (hd < 15)
;                 asm volatile("v_fma_f32 %0, %16, |%8|, %0\n\tv_fma_f32 %1, %16, |%9|, %1\n\tv_fma_f32 %2, %16, |%10|, %2\n\tv_fma_f32 %3, %16, |%11|, %3\n\t"
;                              "v_fma_f32 %4, %16, |%12|, %4\n\tv_fma_f32 %5, %16, |%13|, %5\n\tv_fma_f32 %6, %16, |%14|, %6\n\tv_fma_f32 %7, %16, |%15|, %7"
;                              : "+v"(sc0[0]), "+v"(sc0[1]), "+v"(sc0[2]), "+v"(sc0[3]), "+v"(sc1[0]), "+v"(sc1[1]), "+v"(sc1[2]), "+v"(sc1[3])
;                              : "v"(c0[0]), "v"(c0[1]), "v"(c0[2]), "v"(c0[3]), "v"(c1[0]), "v"(c1[1]), "v"(c1[2]), "v"(c1[3]), "v"(wv[hd]), "v"(n0), "v"(n1));
;             else
;                 asm volatile("s_nop 15\n\ts_nop 15\n\t"
;                              "v_fma_f32 %0, %16, |%8|, %0\n\tv_fma_f32 %1, %16, |%9|, %1\n\tv_fma_f32 %2, %16, |%10|, %2\n\tv_fma_f32 %3, %16, |%11|, %3\n\t"
;                              "v_fma_f32 %4, %16, |%12|, %4\n\tv_fma_f32 %5, %16, |%13|, %5\n\tv_fma_f32 %6, %16, |%14|, %6\n\tv_fma_f32 %7, %16, |%15|, %7"
;                              : "+v"(sc0[0]), "+v"(sc0[1]), "+v"(sc0[2]), "+v"(sc0[3]), "+v"(sc1[0]), "+v"(sc1[1]), "+v"(sc1[2]), "+v"(sc1[3])
;                              : "v"(c0[0]), "v"(c0[1]), "v"(c0[2]), "v"(c0[3]), "v"(c1[0]), "v"(c1[1]), "v"(c1[2]), "v"(c1[3]), "v"(wv[hd]));
;             c0 = n0; c1 = n1;
;         }
;         unsigned k32[8]; int keyi[8];
; #pragma unroll
;         for (int j = 0; j < 4; ++j) { k32[j] = f2key(sc0[j]); k32[4 + j] = f2key(sc1[j]); keyi[j] = kb + quad * 4 + j; keyi[4 + j] = kb + 16 + quad * 4 + j; }
;         int np = 0;
; #pragma unroll
	v_mfma_f32_16x16x32_bf16 v[112:115], v[44:47], v[252:255], v[112:115]
	v_mfma_f32_16x16x32_bf16 v[104:107], v[52:55], v[252:255], v[104:107]
	v_fma_f32 v36, v96, |v116|, v36
	v_fma_f32 v37, v96, |v117|, v37
	v_fma_f32 v38, v96, |v118|, v38
	v_fma_f32 v39, v96, |v119|, v39
	v_fma_f32 v32, v96, |v64|, v32
	v_fma_f32 v33, v96, |v65|, v33
	v_fma_f32 v34, v96, |v66|, v34
	v_fma_f32 v68, v96, |v67|, v68
	ds_read_b128 v[248:251], v103 offset:1920
	ds_read_b128 v[252:255], v103 offset:1984
	s_waitcnt lgkmcnt(3)
	v_mfma_f32_16x16x32_bf16 v[116:119], v[40:43], v[240:243], 0
	v_mfma_f32_16x16x32_bf16 v[64:67], v[48:51], v[240:243], 0
	s_waitcnt lgkmcnt(2)
	v_mfma_f32_16x16x32_bf16 v[116:119], v[44:47], v[244:247], v[116:119]
	v_mfma_f32_16x16x32_bf16 v[64:67], v[52:55], v[244:247], v[64:67]
	v_fma_f32 v36, v97, |v112|, v36
	v_fma_f32 v37, v97, |v113|, v37
	v_fma_f32 v38, v97, |v114|, v38
	v_fma_f32 v39, v97, |v115|, v39
	v_fma_f32 v32, v97, |v104|, v32
	v_fma_f32 v33, v97, |v105|, v33
	v_fma_f32 v34, v97, |v106|, v34
	v_fma_f32 v68, v97, |v107|, v68
	s_waitcnt lgkmcnt(1)
	v_mfma_f32_16x16x32_bf16 v[40:43], v[40:43], v[248:251], 0
	s_waitcnt lgkmcnt(0)
	v_mfma_f32_16x16x32_bf16 v[40:43], v[44:47], v[252:255], v[40:43]
	v_mfma_f32_16x16x32_bf16 v[44:47], v[48:51], v[248:251], 0
	v_mfma_f32_16x16x32_bf16 v[44:47], v[52:55], v[252:255], v[44:47]
	v_fma_f32 v36, v98, |v116|, v36
	v_fma_f32 v37, v98, |v117|, v37
	v_fma_f32 v38, v98, |v118|, v38
	v_fma_f32 v39, v98, |v119|, v39
	v_fma_f32 v32, v98, |v64|, v32
	v_fma_f32 v33, v98, |v65|, v33
	v_fma_f32 v34, v98, |v66|, v34
	v_fma_f32 v68, v98, |v67|, v68
	s_nop 0
	s_nop 15
	s_nop 15
	v_fma_f32 v36, v99, |v40|, v36
	v_fma_f32 v37, v99, |v41|, v37
	v_fma_f32 v38, v99, |v42|, v38
	v_fma_f32 v39, v99, |v43|, v39
	v_fma_f32 v32, v99, |v44|, v32
	v_fma_f32 v33, v99, |v45|, v33
	v_fma_f32 v34, v99, |v46|, v34
	v_fma_f32 v68, v99, |v47|, v68
	s_nop 4
	v_lshl_add_u32 v43, s28, 8, v100
	v_ashrrev_i32_e32 v45, 31, v36
	v_ashrrev_i32_e32 v46, 31, v37
	v_or_b32_e32 v45, 0x80000000, v45
	v_or_b32_e32 v46, 0x80000000, v46
	v_xor_b32_e32 v154, v45, v36
	v_xor_b32_e32 v44, v46, v37
	v_ashrrev_i32_e32 v45, 31, v38
	v_ashrrev_i32_e32 v46, 31, v39
	v_or_b32_e32 v45, 0x80000000, v45
	v_or_b32_e32 v46, 0x80000000, v46
	v_xor_b32_e32 v42, v45, v38
	v_xor_b32_e32 v40, v46, v39
	v_ashrrev_i32_e32 v45, 31, v32
	v_ashrrev_i32_e32 v46, 31, v33
	v_or_b32_e32 v45, 0x80000000, v45
	v_or_b32_e32 v46, 0x80000000, v46
	v_xor_b32_e32 v38, v45, v32
	v_xor_b32_e32 v36, v46, v33
	v_ashrrev_i32_e32 v45, 31, v34
	v_ashrrev_i32_e32 v46, 31, v68
	v_or_b32_e32 v45, 0x80000000, v45
	v_or_b32_e32 v46, 0x80000000, v46
	v_xor_b32_e32 v34, v45, v34
	v_xor_b32_e32 v32, v46, v68
	v_or_b32_e32 v41, 2, v43
	v_or_b32_e32 v107, 3, v43
	v_or_b32_e32 v106, 16, v43
	v_or_b32_e32 v35, 17, v43
	v_or_b32_e32 v105, 18, v43
	v_or_b32_e32 v104, 19, v43
	v_cmp_le_i32_e64 s[24:25], v43, v56
	v_cmp_lt_i32_e64 s[22:23], v43, v56
	v_cmp_le_i32_e64 s[20:21], v41, v56
	v_cmp_le_i32_e64 s[18:19], v107, v56
	v_cmp_le_i32_e64 s[16:17], v106, v56
	v_cmp_le_i32_e64 s[14:15], v35, v56
	v_cmp_le_i32_e64 s[12:13], v105, v56
	v_cmp_gt_u32_e64 s[10:11], v154, v101
	v_cmp_gt_u32_e32 vcc, v44, v101
	s_and_b64 s[10:11], s[24:25], s[10:11]
	v_cndmask_b32_e64 v45, 0, 1, s[10:11]
	s_and_b64 vcc, s[22:23], vcc
	v_addc_co_u32_e32 v45, vcc, 0, v45, vcc
	v_cmp_gt_u32_e64 s[10:11], v42, v101
	v_cmp_gt_u32_e32 vcc, v40, v101
	s_and_b64 s[10:11], s[20:21], s[10:11]
	v_cndmask_b32_e64 v46, 0, 1, s[10:11]
	s_and_b64 vcc, s[18:19], vcc
	v_addc_co_u32_e32 v45, vcc, v45, v46, vcc
	v_cmp_gt_u32_e64 s[10:11], v38, v101
	v_cmp_gt_u32_e32 vcc, v36, v101
	s_and_b64 s[10:11], s[16:17], s[10:11]
	v_cndmask_b32_e64 v46, 0, 1, s[10:11]
	s_and_b64 vcc, s[14:15], vcc
	v_addc_co_u32_e32 v45, vcc, v45, v46, vcc
	v_cmp_le_i32_e64 s[10:11], v104, v56
	v_cmp_gt_u32_e64 s[26:27], v34, v101
	v_cmp_gt_u32_e32 vcc, v32, v101
	s_and_b64 s[26:27], s[12:13], s[26:27]
	v_cndmask_b32_e64 v46, 0, 1, s[26:27]
	s_and_b64 vcc, s[10:11], vcc
	v_addc_co_u32_e32 v33, vcc, v45, v46, vcc
	s_bitcmp0_b32 s28, 0
	s_cselect_b32 s30, 16, 48
	v_cmp_ne_u32_e32 vcc, 0, v33
	s_and_saveexec_b64 s[26:27], vcc
	v_lshl_add_u32 v37, s30, 2, v81
	ds_add_u32 v37, v33
	s_or_b64 exec, exec, s[26:27]
	s_waitcnt lgkmcnt(0)
	s_barrier
	s_mov_b64 s[26:27], 0
	s_and_saveexec_b64 s[28:29], s[6:7]
	s_cbranch_execz .LBB0_640
	v_lshl_add_u32 v33, s30, 2, v82
	ds_read_b32 v37, v82
	ds_read_b32 v33, v33
	s_waitcnt lgkmcnt(0)
	v_add_u32_e32 v33, v33, v37
	v_cmp_lt_u32_e32 vcc, s73, v33
	s_and_b64 s[26:27], vcc, exec

; __global__ void __launch_bounds__(512, 2) mega(Params p_unused) {
;     ...
;         const int qx = item >> 16, n = item & 0xFFFF;
;         if (n < 256) {
.LBB0_803:
	s_and_b64 vcc, exec, s[4:5]
	s_cbranch_vccz .LBB0_615
; #define LAS __attribute__((address_space(3)))
; #define GAS __attribute__((address_space(1)))
; __device__ __forceinline__ int opaque_tid() { int t = threadIdx.x; asm volatile("" : "+v"(t)); return t; }
; __device__ void attn_pair_block(LAS unsigned char* lds, const bf16_t* Qp, const bf16_t* Kp, const bf16_t* Vp, int qb, bf16_t* outp, const float negMB) {
;     const int tid = opaque_tid(), wid = __builtin_amdgcn_readfirstlane(tid >> 6), lane = tid & 63, c = lane & 31, h = lane >> 5;
;     const int stw = wid >> 2;
;     const int q0 = qb * 128 + (wid & 3) * 32, qpos = q0 + c;
;     bf16x8 qf[8];
; #pragma unroll
;     for (int ks = 0; ks < 8; ++ks) qf[ks] = *(const GAS bf16x8*)(Qp + (size_t)qpos * 1024 + ks * 16 + h * 8);
;     f32x16 o[4];
; #pragma unroll
;     for (int d = 0; d < 4; ++d)
; #pragma unroll
;         for (int r = 0; r < 16; ++r) o[d][r] = 0.f;
;     float lrun = 0.f;
;     const int nt = 2 * (qb + 1);
;     const int my_last = (q0 + 31) >> 6;
;     u32x4 kr[2], vr[4];
;     ...
;     PB_GLOAD(0); PB_LSTORE(0);
;     __syncthreads();
;     const int kread = (32 * stw + c) * KP + h * 16;
;     const int vread = (4 * h + ((lane & 15) >> 2)) * VP2 + stw * 256 + ((lane >> 4) & 1) * 32 + (lane & 3) * 8;
;     LAS unsigned char* xmine = lds + XBUF_OFF + wid * 2048 + lane * 16;
;     const LAS unsigned char* xother = lds + XBUF_OFF + (wid ^ 4) * 2048 + lane * 16;
;     for (int j = 0; j < nt; ++j) {
;         LAS unsigned char* kb = lds + (j & 1) * PSTAGE; LAS unsigned char* vb = kb + KBYTES;
;         if (j + 1 < nt) PB_GLOAD(j + 1);
	s_lshr_b32 s4, s83, 1
	s_lshr_b32 s6, s82, 17
	s_sub_i32 s16, 0x7f, s4
	s_and_b32 s8, s82, 1
	s_lshl_b32 s4, s84, 14
	s_lshl_b32 s5, s6, 1
	s_and_b32 s11, s4, 0x4000
	s_or_b32 s10, s5, s8
	s_lshl_b32 s4, s11, 11
	s_lshl_b32 s5, s10, 8
	s_add_u32 s7, s50, s4
	s_addc_u32 s9, s51, 0
	v_and_b32_e32 v50, 64, v214
	v_lshlrev_b32_e32 v50, 2, v50
	v_lshrrev_b32_e32 v51, 1, v214
	v_and_b32_e32 v51, 0xc0, v51
	v_or_b32_e32 v50, v50, v51
	v_and_b32_e32 v51, 63, v214
	v_or_b32_e32 v50, v50, v51
	s_add_u32 s4, s7, s5
	s_addc_u32 s5, s9, 0
	v_lshlrev_b32_e32 v28, 4, v50
	v_and_b32_e32 v40, 0xf0, v28
	v_mov_b32_e32 v41, v155
	v_ashrrev_i32_e32 v42, 4, v50
	v_add_u32_e32 v29, 0x200, v50
	s_lshl_b32 s23, s6, 9
	v_lshl_add_u64 v[16:17], s[4:5], 0, v[40:41]
	v_ashrrev_i32_e32 v43, 31, v42
	v_ashrrev_i32_e32 v160, 4, v29
	s_add_u32 s6, s7, s23
	v_lshl_add_u64 v[158:159], v[16:17], 0, s[58:59]
	v_lshlrev_b64 v[44:45], 11, v[42:43]
	v_ashrrev_i32_e32 v161, 31, v160
	s_addc_u32 s7, s9, 0
	s_add_u32 s100, s4, 0x1cc40000
	s_addc_u32 s101, s5, 0
	s_add_u32 s64, s6, 0x20c20000
	s_addc_u32 s65, s7, 0
	v_lshl_add_u64 v[24:25], v[158:159], 0, v[44:45]
	v_lshlrev_b64 v[16:17], 11, v[160:161]
	v_and_b32_e32 v162, 0x1f0, v28
	v_mov_b32_e32 v163, v155
	v_ashrrev_i32_e32 v166, 5, v50
	v_lshl_add_u64 v[26:27], v[158:159], 0, v[16:17]
	global_load_dwordx4 v[16:19], v[24:25], off
	global_load_dwordx4 v[20:23], v[26:27], off
	v_lshl_add_u64 v[24:25], s[6:7], 0, v[162:163]
	v_ashrrev_i32_e32 v167, 31, v166
	v_ashrrev_i32_e32 v168, 5, v29
	v_lshl_add_u64 v[164:165], v[24:25], 0, s[60:61]
	v_lshlrev_b64 v[24:25], 11, v[166:167]
	v_ashrrev_i32_e32 v169, 31, v168
	v_readfirstlane_b32 s6, v50
	v_lshl_add_u64 v[32:33], v[164:165], 0, v[24:25]
	v_lshlrev_b64 v[24:25], 11, v[168:169]
	s_ashr_i32 s7, s6, 6
	v_lshl_add_u64 v[34:35], v[164:165], 0, v[24:25]
	global_load_dwordx4 v[24:27], v[32:33], off
	global_load_dwordx4 v[28:31], v[34:35], off
	v_add_u32_e32 v32, 0x400, v50
	v_add_u32_e32 v36, 0x600, v50
	s_lshl_b32 s12, s7, 5
	v_ashrrev_i32_e32 v170, 5, v32
	v_ashrrev_i32_e32 v172, 5, v36
	v_lshl_add_u32 v250, v42, 11, v40
	v_lshl_add_u32 v251, v160, 11, v40
	v_lshl_add_u32 v246, v166, 11, v162
	v_lshl_add_u32 v247, v168, 11, v162
	v_lshl_add_u32 v248, v170, 11, v162
	v_lshl_add_u32 v249, v172, 11, v162
	s_lshl_b32 s9, s16, 7
	s_and_b32 s12, s12, 0x60
	v_ashrrev_i32_e32 v171, 31, v170
	v_ashrrev_i32_e32 v173, 31, v172
	v_and_b32_e32 v43, 31, v50
	s_or_b32 s18, s12, s9
	v_lshlrev_b64 v[32:33], 11, v[170:171]
	v_lshlrev_b64 v[36:37], 11, v[172:173]
	v_or_b32_e32 v156, s18, v43
	v_lshl_add_u64 v[32:33], v[164:165], 0, v[32:33]
	v_lshl_add_u64 v[36:37], v[164:165], 0, v[36:37]
	v_bfe_u32 v51, v50, 5, 1
	v_lshlrev_b32_e32 v154, 11, v156
	global_load_dwordx4 v[32:35], v[32:33], off
	v_lshl_add_u64 v[46:47], s[4:5], 0, v[154:155]
	global_load_dwordx4 v[36:39], v[36:37], off
	v_lshlrev_b32_e32 v154, 4, v51
	v_lshl_add_u64 v[46:47], v[46:47], 0, v[154:155]
	v_lshl_add_u64 v[48:49], v[46:47], 0, s[56:57]
	v_add_co_u32_e32 v46, vcc, s78, v46
	v_add_u32_e32 v185, 0, v40
	s_nop 0
	v_addc_co_u32_e32 v47, vcc, 0, v47, vcc
	global_load_dwordx4 v[120:123], v[48:49], off offset:32
	global_load_dwordx4 v[116:119], v[48:49], off offset:64
	global_load_dwordx4 v[112:115], v[48:49], off offset:96
	global_load_dwordx4 v[108:111], v[48:49], off offset:128
	global_load_dwordx4 v[100:103], v[48:49], off offset:160
	global_load_dwordx4 v[104:107], v[48:49], off offset:192
	global_load_dwordx4 v[124:127], v[46:47], off
	global_load_dwordx4 v[96:99], v[48:49], off offset:224
	v_mul_lo_u32 v186, v42, s79
	v_add_u32_e32 v40, v185, v186
	v_mul_lo_u32 v187, v160, s79
	v_mul_lo_u32 v188, v166, s80
	s_lshl_b32 s4, s7, 11
	s_ashr_i32 s12, s6, 8
	v_mul_lo_u32 v189, v168, s80
	s_add_i32 s13, s81, s4
	s_xor_b32 s4, s4, 0x2000
	v_mul_lo_u32 v190, v170, s80
	v_mul_lo_u32 v191, v172, s80
	s_lshr_b32 s21, s18, 6
	s_lshl_b32 s19, s12, 5
	s_and_b32 s14, s6, 0xffffff00
	s_add_i32 s15, s81, s4
	s_cmpk_lt_u32 s6, 0x100
	s_cselect_b64 s[6:7], -1, 0
	s_cmp_eq_u32 s12, 1
	v_lshlrev_b32_e32 v161, 2, v51
	s_cselect_b64 s[4:5], -1, 0
	s_and_b32 s9, s83, 0xfffe
	s_sub_i32 s22, 0xff, s9
	s_lshl_b32 s9, s82, 9
	s_lshl_b32 s8, s8, 8
	s_and_b32 s54, s9, 0x2000000
	s_or_b32 s8, s8, s23
	s_add_u32 s8, s50, s8
	s_addc_u32 s9, s51, 0
	v_and_b32_e32 v41, 63, v50
	v_lshlrev_b32_e32 v46, 3, v50
	v_and_b32_e32 v173, 24, v46
	v_lshlrev_b32_e32 v163, 4, v41
	s_mov_b32 s17, 63
	s_mov_b32 s20, 0
	v_sub_u32_e32 v183, v156, v161
	v_mov_b32_e32 v167, 0
	s_waitcnt vmcnt(13)
	ds_write_b128 v40, v[16:19]
	v_add_u32_e32 v16, v185, v187
	s_waitcnt vmcnt(12)
	ds_write_b128 v16, v[20:23]
	v_add_u32_e32 v16, 0, v162
	v_add_u32_e32 v17, v16, v188
	v_and_b32_e32 v18, 15, v50
	v_mov_b32_e32 v19, v155
	v_mov_b32_e32 v20, v155
	v_mov_b32_e32 v21, v155
	v_mov_b32_e32 v22, v155
	v_mov_b32_e32 v23, v155
	s_waitcnt vmcnt(11)
	ds_write_b128 v17, v[24:27] offset:17408
	v_add_u32_e32 v17, v16, v189
	s_waitcnt vmcnt(10)
	ds_write_b128 v17, v[28:31] offset:17408
	v_add_u32_e32 v17, v16, v190
	v_add_u32_e32 v16, v16, v191
	v_mov_b32_e32 v30, v155
	v_mov_b32_e32 v31, v155
	v_mov_b32_e32 v24, v155
	v_mov_b32_e32 v25, v155
	v_mov_b32_e32 v26, v155
	v_mov_b32_e32 v27, v155
	v_mov_b32_e32 v28, v155
	v_mov_b32_e32 v29, v155
	s_waitcnt vmcnt(9)
	ds_write_b128 v17, v[32:35] offset:17408
	s_waitcnt vmcnt(8)
	ds_write_b128 v16, v[36:39] offset:17408
	v_or_b32_e32 v16, s19, v43
	v_mul_lo_u32 v192, v16, s79
	v_lshrrev_b32_e32 v16, 2, v50
	v_and_or_b32 v16, v16, 3, v161
	v_mul_u32_u24_e32 v169, 0x240, v16
	v_lshlrev_b32_e32 v16, 1, v50
	v_and_b32_e32 v171, 32, v16
	v_lshl_add_u64 v[16:17], s[54:55], 0, v[44:45]
	v_lshl_or_b32 v16, v18, 4, v16
	v_lshl_add_u64 v[16:17], s[8:9], 0, v[16:17]
	v_lshl_add_u64 v[174:175], v[16:17], 0, s[62:63]
	v_mov_b32_e32 v16, v155
	v_mov_b32_e32 v17, v155
	v_mov_b32_e32 v18, v155
	v_mov_b64_e32 v[46:47], v[30:31]
	v_mov_b64_e32 v[62:63], v[30:31]
	v_mov_b64_e32 v[78:79], v[30:31]
	v_mov_b64_e32 v[44:45], v[28:29]
	v_mov_b64_e32 v[42:43], v[26:27]
	v_mov_b64_e32 v[40:41], v[24:25]
	v_mov_b64_e32 v[38:39], v[22:23]
	v_mov_b64_e32 v[36:37], v[20:21]
	v_mov_b64_e32 v[34:35], v[18:19]
	v_mov_b64_e32 v[32:33], v[16:17]
	v_mov_b64_e32 v[60:61], v[28:29]
	v_mov_b64_e32 v[58:59], v[26:27]
	v_mov_b64_e32 v[56:57], v[24:25]
	v_mov_b64_e32 v[54:55], v[22:23]
	v_mov_b64_e32 v[52:53], v[20:21]
	v_mov_b64_e32 v[50:51], v[18:19]
	v_mov_b64_e32 v[48:49], v[16:17]
	v_mov_b64_e32 v[76:77], v[28:29]
	v_mov_b64_e32 v[74:75], v[26:27]
	v_mov_b64_e32 v[72:73], v[24:25]
	v_mov_b64_e32 v[70:71], v[22:23]
	v_mov_b64_e32 v[68:69], v[20:21]
	v_mov_b64_e32 v[66:67], v[18:19]
	v_mov_b64_e32 v[64:65], v[16:17]
	v_add3_u32 v88, v160, s17, 1
	v_ashrrev_i32_e32 v89, 31, v88
	v_lshlrev_b64 v[88:89], 11, v[88:89]
	v_lshl_add_u64 v[88:89], v[158:159], 0, v[88:89]
	global_load_dwordx4 v[128:131], v[174:175], off
	global_load_dwordx4 v[136:139], v[88:89], off
	s_waitcnt vmcnt(2)
	s_waitcnt lgkmcnt(0)
	s_barrier
	s_branch .LBB0_806

; #define LAS __attribute__((address_space(3)))
; __device__ void attn_pair_block(LAS unsigned char* lds, const bf16_t* Qp, const bf16_t* Kp, const bf16_t* Vp, int qb, bf16_t* outp, const float negMB) {
;     ...
;     for (int j = 0; j < nt; ++j) {
;         LAS unsigned char* kb = lds + (j & 1) * PSTAGE; LAS unsigned char* vb = kb + KBYTES;
;         if (j + 1 < nt) PB_GLOAD(j + 1);
;         const bool act = j <= my_last;
;         bf16x8 pown[2];
;         if (act) {
;             f32x16 s0;
; #pragma unroll
;             for (int r = 0; r < 16; ++r) s0[r] = negMB;
; #pragma unroll
;             for (int ks = 0; ks < 8; ++ks) { const bf16x8 k0 = *(const LAS bf16x8*)(kb + kread + ks * 32); s0 = __builtin_amdgcn_mfma_f32_32x32x16_bf16(k0, qf[ks], s0, 0, 0, 0); }
;             __builtin_amdgcn_sched_group_barrier(0x100, 3, 0);
; #pragma unroll
;             for (int i = 0; i < 8; ++i) { __builtin_amdgcn_sched_group_barrier(0x008, 1, 0); __builtin_amdgcn_sched_group_barrier(0x100, 1, 0); }
;             if (j * 64 + 63 > q0) {
;                 const int kbase = j * 64 + 32 * stw + 4 * h;
; #pragma unroll
;                 for (int r = 0; r < 16; ++r) { const int key = kbase + (r & 3) + 8 * (r >> 2); if (key > qpos) s0[r] = -INFINITY; }
.Lpb_tail:
	s_waitcnt lgkmcnt(0)
	s_barrier
	s_add_i32 s17, s17, 64
	s_cmp_eq_u32 s22, s20
	s_cbranch_scc1 .LBB0_812
.LBB0_806:
	global_load_dwordx4 v[132:135], v246, s[64:65]
	global_load_dwordx4 v[144:147], v247, s[64:65]
	global_load_dwordx4 v[140:143], v248, s[64:65]
	global_load_dwordx4 v[148:151], v249, s[64:65]
	s_add_u32 s64, s64, 0x20000
	s_addc_u32 s65, s65, 0
	s_bitcmp1_b32 s20, 0
	s_cselect_b32 s8, 0xd400, 0
	s_add_i32 s23, s8, 0
	s_xor_b32 s24, s8, 0xd400
	v_add_u32_e32 v240, s24, v185
	v_add_u32_e32 v241, v240, v186
	v_add_u32_e32 v240, v240, v187
	s_waitcnt vmcnt(5)
	ds_write_b128 v241, v[128:131]
	s_waitcnt vmcnt(4)
	ds_write_b128 v240, v[136:139]
	s_cmp_le_u32 s20, s21
	s_cselect_b64 s[8:9], -1, 0
	s_cmp_gt_u32 s20, s21
	s_cbranch_scc1 .LBB0_810
	v_add3_u32 v193, s23, v192, v154
	ds_read_b128 v[194:197], v193
	ds_read_b128 v[198:201], v193 offset:32
	ds_read_b128 v[202:205], v193 offset:64
	s_cmp_le_u32 s17, s18
	s_waitcnt vmcnt(7) lgkmcnt(2)
	v_mfma_f32_32x32x16_bf16 v[80:95], v[194:197], v[124:127], v[0:15]
	ds_read_b128 v[194:197], v193 offset:96
	s_waitcnt lgkmcnt(2)
	v_mfma_f32_32x32x16_bf16 v[80:95], v[198:201], v[120:123], v[80:95]
	ds_read_b128 v[198:201], v193 offset:128
	s_waitcnt lgkmcnt(2)
	v_mfma_f32_32x32x16_bf16 v[80:95], v[202:205], v[116:119], v[80:95]
	ds_read_b128 v[202:205], v193 offset:160
	s_waitcnt lgkmcnt(2)
	v_mfma_f32_32x32x16_bf16 v[80:95], v[194:197], v[112:115], v[80:95]
	ds_read_b128 v[194:197], v193 offset:192
	s_waitcnt lgkmcnt(2)
	v_mfma_f32_32x32x16_bf16 v[80:95], v[198:201], v[108:111], v[80:95]
	ds_read_b128 v[198:201], v193 offset:224
	s_waitcnt lgkmcnt(2)
	v_mfma_f32_32x32x16_bf16 v[80:95], v[202:205], v[100:103], v[80:95]
	s_waitcnt lgkmcnt(1)
	v_mfma_f32_32x32x16_bf16 v[80:95], v[194:197], v[104:107], v[80:95]
	s_waitcnt vmcnt(6) lgkmcnt(0)
	v_mfma_f32_32x32x16_bf16 v[80:95], v[198:201], v[96:99], v[80:95]
	s_cbranch_scc1 .LBB0_809
	s_add_i32 s24, s19, s17
	s_sub_i32 s25, s24, 63
	v_cmp_lt_i32_e32 vcc, s25, v183
	s_nop 7
	v_cndmask_b32_e32 v81, v182, v81, vcc
	v_cmp_le_i32_e32 vcc, s25, v183
	s_sub_i32 s25, s24, 61
	s_nop 0
	v_cndmask_b32_e32 v80, v182, v80, vcc
	v_cmp_le_i32_e32 vcc, s25, v183
	s_sub_i32 s25, s24, 60
	s_nop 0
	v_cndmask_b32_e32 v82, v182, v82, vcc
	v_cmp_le_i32_e32 vcc, s25, v183
	s_sub_i32 s25, s24, 55
	s_nop 0
	v_cndmask_b32_e32 v83, v182, v83, vcc
	v_cmp_le_i32_e32 vcc, s25, v183
	s_sub_i32 s25, s24, 54
	s_nop 0
	v_cndmask_b32_e32 v84, v182, v84, vcc
	v_cmp_le_i32_e32 vcc, s25, v183
	s_sub_i32 s25, s24, 53
	s_nop 0
	v_cndmask_b32_e32 v85, v182, v85, vcc
	v_cmp_le_i32_e32 vcc, s25, v183
	s_sub_i32 s25, s24, 52
	s_nop 0
	v_cndmask_b32_e32 v86, v182, v86, vcc
	v_cmp_le_i32_e32 vcc, s25, v183
	s_sub_i32 s25, s24, 47
	s_nop 0
	v_cndmask_b32_e32 v87, v182, v87, vcc
	v_cmp_le_i32_e32 vcc, s25, v183
	s_sub_i32 s25, s24, 46
	s_nop 0
	v_cndmask_b32_e32 v88, v182, v88, vcc
	v_cmp_le_i32_e32 vcc, s25, v183
	s_sub_i32 s25, s24, 45
	s_nop 0
	v_cndmask_b32_e32 v89, v182, v89, vcc
	v_cmp_le_i32_e32 vcc, s25, v183
	s_sub_i32 s25, s24, 44
	s_nop 0
	v_cndmask_b32_e32 v90, v182, v90, vcc
	v_cmp_le_i32_e32 vcc, s25, v183
	s_sub_i32 s25, s24, 39
	s_nop 0
	v_cndmask_b32_e32 v91, v182, v91, vcc
	v_cmp_le_i32_e32 vcc, s25, v183
	s_sub_i32 s25, s24, 38
	s_nop 0
	v_cndmask_b32_e32 v92, v182, v92, vcc
	v_cmp_le_i32_e32 vcc, s25, v183
	s_sub_i32 s25, s24, 37
	s_sub_i32 s24, s24, 36
	v_cndmask_b32_e32 v93, v182, v93, vcc
	v_cmp_le_i32_e32 vcc, s25, v183
	s_nop 1
	v_cndmask_b32_e32 v94, v182, v94, vcc
	v_cmp_le_i32_e32 vcc, s24, v183
	s_nop 1
	v_cndmask_b32_e32 v95, v182, v95, vcc

; #define LAS __attribute__((address_space(3)))
; __device__ void attn_pair_block(LAS unsigned char* lds, const bf16_t* Qp, const bf16_t* Kp, const bf16_t* Vp, int qb, bf16_t* outp, const float negMB) {
;     ...
;         if (act) {
;             bf16x8 poth[2];
; #pragma unroll
;             for (int s2 = 0; s2 < 2; ++s2) poth[s2] = *(const LAS bf16x8*)(xother + s2 * 1024);
;             __builtin_amdgcn_s_setprio(1);
; #pragma unroll
;             for (int st = 0; st < 2; ++st)
; #pragma unroll
;                 for (int s2 = 0; s2 < 2; ++s2)
; #pragma unroll
;                     for (int d = 0; d < 4; ++d) {
;                         const s16x4 lo = __builtin_amdgcn_ds_read_tr16_b64_v4i16((LAS s16x4*)(vb + vread + (32 * st + 16 * s2) * VP2 + d * 64));
;                         const s16x4 hi = __builtin_amdgcn_ds_read_tr16_b64_v4i16((LAS s16x4*)(vb + vread + (32 * st + 16 * s2 + 8) * VP2 + d * 64));
;                         const bf16x8 vf = __builtin_shufflevector(lo, hi, 0, 1, 2, 3, 4, 5, 6, 7);
;                         const bf16x8 pfr = (st == stw) ? pown[s2] : poth[s2];
;                         o[d] = __builtin_amdgcn_mfma_f32_32x32x16_bf16(vf, pfr, o[d], 0, 0, 0);
;                     }
;             __builtin_amdgcn_sched_group_barrier(0x100, 8, 1);
; #pragma unroll
;             for (int i = 0; i < 16; ++i) { __builtin_amdgcn_sched_group_barrier(0x008, 1, 1); __builtin_amdgcn_sched_group_barrier(0x100, 2, 1); }
;             __builtin_amdgcn_s_setprio(0);
;         }
;         if (j + 1 < nt) PB_LSTORE((j + 1) & 1);
.LBB0_810:
	s_waitcnt lgkmcnt(0)
	s_barrier
	global_load_dwordx4 v[128:131], v250, s[100:101]
	global_load_dwordx4 v[136:139], v251, s[100:101]
	s_add_u32 s100, s100, 0x20000
	s_addc_u32 s101, s101, 0
	s_andn2_b64 vcc, exec, s[8:9]
	s_cbranch_vccnz .LBB0_805
	v_add_u32_e32 v92, s15, v163
	ds_read_b128 v[88:91], v92
	ds_read_b128 v[92:95], v92 offset:1024
	s_setprio 1
	s_add_i32 s8, s14, s23
	s_mul_i32 s24, s12, 0x4800
	s_sub_i32 s25, 0x4800, s24
	v_add_u32_e32 v193, s8, v169
	v_add3_u32 v193, v193, v171, v173
	v_add_u32_e32 v194, s25, v193
	v_add_u32_e32 v193, s24, v193
	ds_read_b64_tr_b16 v[198:199], v193 offset:17408
	ds_read_b64_tr_b16 v[200:201], v193 offset:22016
	ds_read_b64_tr_b16 v[202:203], v193 offset:17472
	ds_read_b64_tr_b16 v[204:205], v193 offset:22080
	ds_read_b64_tr_b16 v[206:207], v193 offset:17536
	ds_read_b64_tr_b16 v[208:209], v193 offset:22144
	ds_read_b64_tr_b16 v[210:211], v193 offset:17600
	ds_read_b64_tr_b16 v[212:213], v193 offset:22208
	s_add_i32 s24, s20, 1
	s_bitcmp1_b32 s24, 0
	s_cselect_b32 s23, 0xd400, 0
	v_add_u32_e32 v242, s23, v162
	v_add_u32_e32 v243, v242, v188
	v_add_u32_e32 v244, v242, v189
	v_add_u32_e32 v245, v242, v190
	v_add_u32_e32 v242, v242, v191
	s_waitcnt lgkmcnt(6)
	v_mfma_f32_32x32x16_bf16 v[64:79], v[198:201], v[84:87], v[64:79]
	ds_read_b64_tr_b16 v[198:199], v193 offset:26624
	ds_read_b64_tr_b16 v[200:201], v193 offset:31232
	s_waitcnt lgkmcnt(6)
	v_mfma_f32_32x32x16_bf16 v[48:63], v[202:205], v[84:87], v[48:63]
	ds_read_b64_tr_b16 v[202:203], v193 offset:26688
	ds_read_b64_tr_b16 v[204:205], v193 offset:31296
	s_waitcnt lgkmcnt(6)
	v_mfma_f32_32x32x16_bf16 v[32:47], v[206:209], v[84:87], v[32:47]
	ds_read_b64_tr_b16 v[206:207], v193 offset:26752
	ds_read_b64_tr_b16 v[208:209], v193 offset:31360
	s_waitcnt vmcnt(5)
	ds_write_b128 v243, v[132:135] offset:17408
	s_waitcnt lgkmcnt(7)
	v_mfma_f32_32x32x16_bf16 v[16:31], v[210:213], v[84:87], v[16:31]
	ds_read_b64_tr_b16 v[210:211], v193 offset:26816
	ds_read_b64_tr_b16 v[212:213], v193 offset:31424
	s_waitcnt lgkmcnt(7)
	v_mfma_f32_32x32x16_bf16 v[64:79], v[198:201], v[80:83], v[64:79]
	ds_read_b64_tr_b16 v[198:199], v194 offset:17408
	ds_read_b64_tr_b16 v[200:201], v194 offset:22016
	s_waitcnt lgkmcnt(7)
	v_mfma_f32_32x32x16_bf16 v[48:63], v[202:205], v[80:83], v[48:63]
	ds_read_b64_tr_b16 v[202:203], v194 offset:17472
	ds_read_b64_tr_b16 v[204:205], v194 offset:22080
	s_waitcnt vmcnt(4)
	ds_write_b128 v244, v[144:147] offset:17408
	s_waitcnt lgkmcnt(8)
	v_mfma_f32_32x32x16_bf16 v[32:47], v[206:209], v[80:83], v[32:47]
	ds_read_b64_tr_b16 v[206:207], v194 offset:17536
	ds_read_b64_tr_b16 v[208:209], v194 offset:22144
	s_waitcnt lgkmcnt(7)
	v_mfma_f32_32x32x16_bf16 v[16:31], v[210:213], v[80:83], v[16:31]
	ds_read_b64_tr_b16 v[210:211], v194 offset:17600
	ds_read_b64_tr_b16 v[212:213], v194 offset:22208
	s_waitcnt lgkmcnt(7)
	v_mfma_f32_32x32x16_bf16 v[64:79], v[198:201], v[88:91], v[64:79]
	ds_read_b64_tr_b16 v[198:199], v194 offset:26624
	ds_read_b64_tr_b16 v[200:201], v194 offset:31232
	s_waitcnt vmcnt(3)
	ds_write_b128 v245, v[140:143] offset:17408
	s_waitcnt lgkmcnt(8)
	v_mfma_f32_32x32x16_bf16 v[48:63], v[202:205], v[88:91], v[48:63]
	ds_read_b64_tr_b16 v[202:203], v194 offset:26688
	ds_read_b64_tr_b16 v[204:205], v194 offset:31296
	s_waitcnt lgkmcnt(7)
	v_mfma_f32_32x32x16_bf16 v[32:47], v[206:209], v[88:91], v[32:47]
	ds_read_b64_tr_b16 v[206:207], v194 offset:26752
	ds_read_b64_tr_b16 v[208:209], v194 offset:31360
	s_waitcnt lgkmcnt(7)
	v_mfma_f32_32x32x16_bf16 v[16:31], v[210:213], v[88:91], v[16:31]
	ds_read_b64_tr_b16 v[210:211], v194 offset:26816
	ds_read_b64_tr_b16 v[212:213], v194 offset:31424
	s_waitcnt vmcnt(2)
	ds_write_b128 v242, v[148:151] offset:17408
	s_waitcnt lgkmcnt(8)
	v_mfma_f32_32x32x16_bf16 v[64:79], v[198:201], v[92:95], v[64:79]
	s_waitcnt lgkmcnt(5)
	v_mfma_f32_32x32x16_bf16 v[48:63], v[202:205], v[92:95], v[48:63]
	s_waitcnt lgkmcnt(3)
	v_mfma_f32_32x32x16_bf16 v[32:47], v[206:209], v[92:95], v[32:47]
	s_waitcnt lgkmcnt(1)
	v_mfma_f32_32x32x16_bf16 v[16:31], v[210:213], v[92:95], v[16:31]
	s_setprio 0
	s_add_i32 s20, s20, 1
	s_branch .Lpb_tail

; __device__ __forceinline__ void lds_barrier() { asm volatile("s_waitcnt lgkmcnt(0)" ::: "memory"); __builtin_amdgcn_s_barrier(); asm volatile("" ::: "memory"); }
; #define ATT_GLOAD(j) do { _Pragma("unroll") for (int _i = 0; _i < 2; ++_i) { const size_t _o = (size_t)((j) * 64 + srow + 32 * _i) * 1024 + sch * 8; \
;         kr[_i] = *(const GAS u32x4*)(Kp + _o); vr[_i] = *(const GAS u32x4*)(Vp + _o); } } while (0)
; #define ATT_LSTORE(buf) do { _Pragma("unroll") for (int _i = 0; _i < 2; ++_i) { \
;         *(LAS u32x4*)(lds + (buf) * ASTAGE + (srow + 32 * _i) * KP + sch * 16) = kr[_i]; \
;         *(LAS u32x4*)(lds + (buf) * ASTAGE + KBYTES + (srow + 32 * _i) * VP + sch * 16) = vr[_i]; } } while (0)
; template <int MODE>
; __device__ void attn_block(LAS unsigned char* lds, const bf16_t* Qp, const bf16_t* Kp, const bf16_t* Vp, int qb, const unsigned* maskp, const bf16_t* sga, bf16_t* outp, const float negMB) {
;     ...
;     ATT_GLOAD(0); ATT_LSTORE(0);
;     const int kread = c * KP + h * 16;
;     const int vread = (4 * h + ((lane & 15) >> 2)) * VP + ((lane >> 4) & 1) * 32 + (lane & 3) * 8;
;     u32x4 mw4 = {0u, 0u, 0u, 0u};
;     int sj = 0, sp = 2;
;     for (int j = 0; j < nt; ++j) {
;         lds_barrier();
;         const int sn = (sj == 2) ? 0 : sj + 1;
;         if (j + 1 < nt) ATT_GLOAD(j + 1);
.LBB0_858:
	s_cmp_lg_u32 s50, 1
	s_cselect_b64 s[28:29], -1, 0
	s_lshl_b32 s8, s8, 2
	s_mov_b32 s34, 1
	s_add_i32 s53, s49, 4
	s_add_i32 s54, s51, 1
	s_waitcnt vmcnt(3)
	ds_write_b128 v194, v[148:151] offset:37888
	s_waitcnt vmcnt(2)
	ds_write_b128 v196, v[152:155] offset:55296
	s_waitcnt vmcnt(1)
	ds_write_b128 v194, v[160:163] offset:46592
	s_waitcnt vmcnt(0)
	ds_write_b128 v195, v[164:167] offset:55296
	v_or_b32_e32 v194, 2, v168
	v_or_b32_e32 v195, 3, v168
	v_or_b32_e32 v196, 8, v168
	v_or_b32_e32 v197, 9, v168
	v_or_b32_e32 v198, 10, v168
	v_or_b32_e32 v199, 11, v168
	v_or_b32_e32 v200, 16, v168
	v_or_b32_e32 v201, 17, v168
	v_or_b32_e32 v202, 18, v168
	v_or_b32_e32 v203, 19, v168
	v_or_b32_e32 v204, 24, v168
	v_or_b32_e32 v205, 25, v168
	v_or_b32_e32 v206, 26, v168
	v_or_b32_e32 v207, 27, v168
	v_add_u32_e32 v208, 0, v187
	s_mov_b32 s55, 0
	s_add_u32 s100, s24, 0x40000
	s_addc_u32 s101, s25, 0
	v_lshlrev_b32_e32 v240, 11, v14
	v_lshl_or_b32 v240, v190, 1, v240
	v_add_u32_e32 v241, 0x4000000, v240
	v_add_u32_e32 v242, 0x10000, v240
	v_add_u32_e32 v243, 0x4010000, v240
	s_sub_i32 s56, 0, s8
	s_movk_i32 s57, 0xff01
	s_mov_b32 s60, 0
.LBB0_859:
	s_waitcnt lgkmcnt(0)
	s_barrier
	s_add_i32 s8, s57, 0x101
	s_cmp_lt_i32 s8, s53
	s_mov_b32 s58, s34
	s_cselect_b64 s[30:31], -1, 0
	s_cmp_ge_i32 s8, s53
	s_cbranch_scc1 .LBB0_861
	global_load_dwordx4 v[148:151], v240, s[100:101]
	global_load_dwordx4 v[152:155], v241, s[100:101]
	global_load_dwordx4 v[160:163], v242, s[100:101]
	global_load_dwordx4 v[164:167], v243, s[100:101]
	s_add_u32 s100, s100, 0x20000
	s_addc_u32 s101, s101, 0
